# P1 GEMM K-loop: As[b][0] staging pair issued from inside the MFMA block, SP2 waits vmcnt(6)
# speedup vs baseline: 1.0037x; 1.0002x over previous
; #define PG8_STAGE(bufoff, gbase, voff) do { _Pragma("unroll") for (int _i = 0; _i < 2; ++_i) \
;         __builtin_amdgcn_global_load_lds((const unsigned*)((const char*)(gbase) + (voff)[_i]), (PG8_LAS unsigned*)(lds + (bufoff) + ldsw + _i * 8192), 16, 0, 0); } while (0)
; #define PG8_LDA(dst, b, h) do { _Pragma("unroll") for (int m = 0; m < 4; ++m) _Pragma("unroll") for (int k = 0; k < 2; ++k) dst[m][k] = *(const PG8_LAS bf16x8*)(lds + PG8_SA(b, h) + aoff + m * 2048 + k * 1024); } while (0)
; #define PG8_LDB(dst, b, h) do { _Pragma("unroll") for (int n = 0; n < 2; ++n) _Pragma("unroll") for (int k = 0; k < 2; ++k) dst[n][k] = *(const PG8_LAS bf16x8*)(lds + PG8_SB(b, h) + boff + n * 2048 + k * 1024); } while (0)
; #define PG8_MMA(ai, bj, At, Bt) do { __builtin_amdgcn_s_setprio(1); _Pragma("unroll") for (int m = 0; m < 4; ++m) _Pragma("unroll") for (int n = 0; n < 2; ++n) _Pragma("unroll") for (int k = 0; k < 2; ++k) \
;         acc[ai][bj][m][n] = __builtin_amdgcn_mfma_f32_16x16x32_bf16(Bt[n][k], At[m][k], acc[ai][bj][m][n], 0, 0, 0); __builtin_amdgcn_s_setprio(0); } while (0)
; #define PG8_WAIT_V(n) asm volatile("s_waitcnt vmcnt(" #n ")" ::: "memory")
; #define PG8_WAIT_L(n) asm volatile("s_waitcnt lgkmcnt(" #n ")" ::: "memory")
; #define PG8_BAR __builtin_amdgcn_s_barrier()
; #define PG8_SCHED __builtin_amdgcn_sched_barrier(0)
; template <class Epi, class Sched, bool ALIGN_EPI = false, bool SP2 = false>
; __device__ __forceinline__ void gemm_phase(PG8_LAS unsigned char* lds, const Gemm g, const Sched& S, const Epi& E, int wid_in) {
;     ...
;             PG8_LDB(B0, 0, 0); PG8_LDB(B1, 0, 1); PG8_SCHED; PG8_LDA(At, 0, 0); PG8_STAGE(PG8_SA(1, 1), a1 + hstep, voffA);
;             PG8_WAIT_V(8); PG8_WAIT_L(0); PG8_BAR; PG8_MMA(0, 0, At, B0); PG8_MMA(0, 1, At, B1); PG8_BAR; PG8_SCHED;
;             PG8_LDA(At, 0, 1); PG8_STAGE(PG8_SB(0, 0), b2, voffB); PG8_STAGE(PG8_SB(0, 1), b2 + hstep, voffB); PG8_STAGE(PG8_SA(0, 0), a2, voffA);
;             PG8_WAIT_V(8); PG8_WAIT_L(0); PG8_BAR; PG8_MMA(1, 0, At, B0); PG8_MMA(1, 1, At, B1); PG8_BAR; PG8_SCHED;
.LBB0_227:
	ds_read_b128 v[128:131], v171
	ds_read_b128 v[132:135], v171 offset:1024
	ds_read_b128 v[158:161], v171 offset:2048
	ds_read_b128 v[162:165], v171 offset:3072
	ds_read_b128 v[174:177], v172
	ds_read_b128 v[178:181], v172 offset:1024
	ds_read_b128 v[182:185], v172 offset:2048
	ds_read_b128 v[186:189], v172 offset:3072
	s_add_u32 s88, s68, 0xfffc0080
	s_addc_u32 s89, s69, -1
	s_cmp_eq_u32 s94, 12
	s_cselect_b32 s91, s3, s89
	s_cselect_b32 s90, s5, s88
	s_cselect_b32 s89, s81, s93
	s_cselect_b32 s88, s83, s92
	v_lshl_add_u64 v[166:167], s[68:69], 0, v[150:151]
	s_add_i32 m0, s34, 0xc000
	ds_read_b128 v[190:193], v173
	ds_read_b128 v[194:197], v173 offset:1024
	ds_read_b128 v[198:201], v173 offset:2048
	ds_read_b128 v[202:205], v173 offset:3072
	ds_read_b128 v[206:209], v173 offset:4096
	ds_read_b128 v[210:213], v173 offset:5120
	ds_read_b128 v[214:217], v173 offset:6144
	ds_read_b128 v[218:221], v173 offset:7168
	global_load_lds_dwordx4 v[166:167], off
	v_lshl_add_u64 v[166:167], s[68:69], 0, v[152:153]
	s_add_i32 m0, s34, 0xe000
	s_nop 0
	global_load_lds_dwordx4 v[166:167], off
	s_waitcnt vmcnt(8)
	s_waitcnt lgkmcnt(0)
	s_barrier
	s_setprio 1
	s_waitcnt lgkmcnt(0)
	v_mfma_f32_16x16x32_bf16 v[124:127], v[128:131], v[190:193], v[124:127]
	v_mfma_f32_16x16x32_bf16 v[120:123], v[158:161], v[190:193], v[120:123]
	v_mfma_f32_16x16x32_bf16 v[108:111], v[128:131], v[198:201], v[108:111]
	v_mfma_f32_16x16x32_bf16 v[104:107], v[158:161], v[198:201], v[104:107]
	v_mfma_f32_16x16x32_bf16 v[92:95], v[128:131], v[206:209], v[92:95]
	v_mfma_f32_16x16x32_bf16 v[88:91], v[158:161], v[206:209], v[88:91]
	v_mfma_f32_16x16x32_bf16 v[76:79], v[128:131], v[214:217], v[76:79]
	v_mfma_f32_16x16x32_bf16 v[72:75], v[158:161], v[214:217], v[72:75]
	v_mfma_f32_16x16x32_bf16 v[124:127], v[132:135], v[194:197], v[124:127]
	v_mfma_f32_16x16x32_bf16 v[120:123], v[162:165], v[194:197], v[120:123]
	v_mfma_f32_16x16x32_bf16 v[108:111], v[132:135], v[202:205], v[108:111]
	v_mfma_f32_16x16x32_bf16 v[104:107], v[162:165], v[202:205], v[104:107]
	v_mfma_f32_16x16x32_bf16 v[92:95], v[132:135], v[210:213], v[92:95]
	v_mfma_f32_16x16x32_bf16 v[88:91], v[162:165], v[210:213], v[88:91]
	v_mfma_f32_16x16x32_bf16 v[76:79], v[132:135], v[218:221], v[76:79]
	v_mfma_f32_16x16x32_bf16 v[72:75], v[162:165], v[218:221], v[72:75]
	s_setprio 0
	s_setprio 1
	v_mfma_f32_16x16x32_bf16 v[116:119], v[174:177], v[190:193], v[116:119]
	v_mfma_f32_16x16x32_bf16 v[112:115], v[182:185], v[190:193], v[112:115]
	v_mfma_f32_16x16x32_bf16 v[100:103], v[174:177], v[198:201], v[100:103]
	v_mfma_f32_16x16x32_bf16 v[96:99], v[182:185], v[198:201], v[96:99]
	v_mfma_f32_16x16x32_bf16 v[84:87], v[174:177], v[206:209], v[84:87]
	v_mfma_f32_16x16x32_bf16 v[80:83], v[182:185], v[206:209], v[80:83]
	v_mfma_f32_16x16x32_bf16 v[68:71], v[174:177], v[214:217], v[68:71]
	v_mfma_f32_16x16x32_bf16 v[64:67], v[182:185], v[214:217], v[64:67]
	v_mfma_f32_16x16x32_bf16 v[116:119], v[178:181], v[194:197], v[116:119]
	v_mfma_f32_16x16x32_bf16 v[112:115], v[186:189], v[194:197], v[112:115]
	v_mfma_f32_16x16x32_bf16 v[100:103], v[178:181], v[202:205], v[100:103]
	v_mfma_f32_16x16x32_bf16 v[96:99], v[186:189], v[202:205], v[96:99]
	v_mfma_f32_16x16x32_bf16 v[84:87], v[178:181], v[210:213], v[84:87]
	v_mfma_f32_16x16x32_bf16 v[80:83], v[186:189], v[210:213], v[80:83]
	v_mfma_f32_16x16x32_bf16 v[68:71], v[178:181], v[218:221], v[68:71]
	v_mfma_f32_16x16x32_bf16 v[64:67], v[186:189], v[218:221], v[64:67]
	s_setprio 0
	s_barrier
	s_add_i32 s95, s70, s12
	v_lshl_add_u64 v[166:167], s[88:89], 0, v[138:139]
	s_mov_b32 m0, s95
	ds_read_b128 v[190:193], v173 offset:16384
	ds_read_b128 v[194:197], v173 offset:17408
	ds_read_b128 v[198:201], v173 offset:18432
	ds_read_b128 v[202:205], v173 offset:19456
	ds_read_b128 v[206:209], v173 offset:20480
	ds_read_b128 v[210:213], v173 offset:21504
	ds_read_b128 v[214:217], v173 offset:22528
	ds_read_b128 v[218:221], v173 offset:23552
	global_load_lds_dwordx4 v[166:167], off
	s_add_i32 m0, s95, 0x2000
	s_add_u32 vcc_lo, s88, 0x40000
	v_lshl_add_u64 v[222:223], s[88:89], 0, v[142:143]
	s_addc_u32 vcc_hi, s89, 0
	s_add_i32 s95, s71, s12
	global_load_lds_dwordx4 v[222:223], off
	v_lshl_add_u64 v[224:225], vcc, 0, v[138:139]
	s_mov_b32 m0, s95
	v_lshl_add_u64 v[226:227], s[90:91], 0, v[140:141]
	global_load_lds_dwordx4 v[224:225], off
	v_lshl_add_u64 v[224:225], vcc, 0, v[142:143]
	s_add_i32 m0, s95, 0x2000
	s_nop 0
	global_load_lds_dwordx4 v[224:225], off
	s_waitcnt vmcnt(6)
	s_waitcnt lgkmcnt(0)
	s_barrier
; #define PG8_STAGE(bufoff, gbase, voff) do { _Pragma("unroll") for (int _i = 0; _i < 2; ++_i) \
;         __builtin_amdgcn_global_load_lds((const unsigned*)((const char*)(gbase) + (voff)[_i]), (PG8_LAS unsigned*)(lds + (bufoff) + ldsw + _i * 8192), 16, 0, 0); } while (0)
; #define PG8_LDA(dst, b, h) do { _Pragma("unroll") for (int m = 0; m < 4; ++m) _Pragma("unroll") for (int k = 0; k < 2; ++k) dst[m][k] = *(const PG8_LAS bf16x8*)(lds + PG8_SA(b, h) + aoff + m * 2048 + k * 1024); } while (0)
; #define PG8_LDB(dst, b, h) do { _Pragma("unroll") for (int n = 0; n < 2; ++n) _Pragma("unroll") for (int k = 0; k < 2; ++k) dst[n][k] = *(const PG8_LAS bf16x8*)(lds + PG8_SB(b, h) + boff + n * 2048 + k * 1024); } while (0)
; #define PG8_MMA(ai, bj, At, Bt) do { __builtin_amdgcn_s_setprio(1); _Pragma("unroll") for (int m = 0; m < 4; ++m) _Pragma("unroll") for (int n = 0; n < 2; ++n) _Pragma("unroll") for (int k = 0; k < 2; ++k) \
;         acc[ai][bj][m][n] = __builtin_amdgcn_mfma_f32_16x16x32_bf16(Bt[n][k], At[m][k], acc[ai][bj][m][n], 0, 0, 0); __builtin_amdgcn_s_setprio(0); } while (0)
; #define PG8_WAIT_V(n) asm volatile("s_waitcnt vmcnt(" #n ")" ::: "memory")
; #define PG8_WAIT_L(n) asm volatile("s_waitcnt lgkmcnt(" #n ")" ::: "memory")
; #define PG8_BAR __builtin_amdgcn_s_barrier()
; #define PG8_SCHED __builtin_amdgcn_sched_barrier(0)
; template <class Epi, class Sched, bool ALIGN_EPI = false, bool SP2 = false>
; __device__ __forceinline__ void gemm_phase(PG8_LAS unsigned char* lds, const Gemm g, const Sched& S, const Epi& E, int wid_in) {
;     ...
;             PG8_WAIT_V(8); PG8_WAIT_L(0); PG8_BAR; PG8_MMA(1, 0, At, B0); PG8_MMA(1, 1, At, B1); PG8_BAR; PG8_SCHED;
;             PG8_LDB(B0, 1, 0); PG8_LDB(B1, 1, 1); PG8_SCHED; PG8_LDA(At, 1, 0); PG8_STAGE(PG8_SA(0, 1), a2 + hstep, voffA);
;             PG8_WAIT_V(8); PG8_WAIT_L(0); PG8_BAR; PG8_MMA(0, 0, At, B0); PG8_MMA(0, 1, At, B1); PG8_BAR; PG8_SCHED;
	s_setprio 1
	s_waitcnt lgkmcnt(0)
	v_mfma_f32_16x16x32_bf16 v[60:63], v[128:131], v[190:193], v[60:63]
	v_mfma_f32_16x16x32_bf16 v[56:59], v[158:161], v[190:193], v[56:59]
	v_mfma_f32_16x16x32_bf16 v[44:47], v[128:131], v[198:201], v[44:47]
	v_mfma_f32_16x16x32_bf16 v[40:43], v[158:161], v[198:201], v[40:43]
	v_mfma_f32_16x16x32_bf16 v[28:31], v[128:131], v[206:209], v[28:31]
	v_mfma_f32_16x16x32_bf16 v[24:27], v[158:161], v[206:209], v[24:27]
	v_lshl_add_u64 v[224:225], s[90:91], 0, v[136:137]
	s_mov_b32 m0, s34
	v_mfma_f32_16x16x32_bf16 v[12:15], v[128:131], v[214:217], v[12:15]
	global_load_lds_dwordx4 v[224:225], off
	s_mov_b32 m0, s35
	v_mfma_f32_16x16x32_bf16 v[8:11], v[158:161], v[214:217], v[8:11]
	global_load_lds_dwordx4 v[226:227], off
	v_mfma_f32_16x16x32_bf16 v[60:63], v[132:135], v[194:197], v[60:63]
	v_mfma_f32_16x16x32_bf16 v[56:59], v[162:165], v[194:197], v[56:59]
	v_mfma_f32_16x16x32_bf16 v[44:47], v[132:135], v[202:205], v[44:47]
	v_mfma_f32_16x16x32_bf16 v[40:43], v[162:165], v[202:205], v[40:43]
	v_mfma_f32_16x16x32_bf16 v[28:31], v[132:135], v[210:213], v[28:31]
	v_mfma_f32_16x16x32_bf16 v[24:27], v[162:165], v[210:213], v[24:27]
	v_mfma_f32_16x16x32_bf16 v[12:15], v[132:135], v[218:221], v[12:15]
	v_mfma_f32_16x16x32_bf16 v[8:11], v[162:165], v[218:221], v[8:11]
	s_setprio 0
	s_setprio 1
	v_mfma_f32_16x16x32_bf16 v[52:55], v[174:177], v[190:193], v[52:55]
	v_mfma_f32_16x16x32_bf16 v[48:51], v[182:185], v[190:193], v[48:51]
	v_mfma_f32_16x16x32_bf16 v[36:39], v[174:177], v[198:201], v[36:39]
	v_mfma_f32_16x16x32_bf16 v[32:35], v[182:185], v[198:201], v[32:35]
	v_mfma_f32_16x16x32_bf16 v[20:23], v[174:177], v[206:209], v[20:23]
	v_mfma_f32_16x16x32_bf16 v[16:19], v[182:185], v[206:209], v[16:19]
	v_mfma_f32_16x16x32_bf16 v[4:7], v[174:177], v[214:217], v[4:7]
	v_mfma_f32_16x16x32_bf16 v[0:3], v[182:185], v[214:217], v[0:3]
	v_mfma_f32_16x16x32_bf16 v[52:55], v[178:181], v[194:197], v[52:55]
	v_mfma_f32_16x16x32_bf16 v[48:51], v[186:189], v[194:197], v[48:51]
	v_mfma_f32_16x16x32_bf16 v[36:39], v[178:181], v[202:205], v[36:39]
	v_mfma_f32_16x16x32_bf16 v[32:35], v[186:189], v[202:205], v[32:35]
	v_mfma_f32_16x16x32_bf16 v[20:23], v[178:181], v[210:213], v[20:23]
	v_mfma_f32_16x16x32_bf16 v[16:19], v[186:189], v[210:213], v[16:19]
	v_mfma_f32_16x16x32_bf16 v[4:7], v[178:181], v[218:221], v[4:7]
	v_mfma_f32_16x16x32_bf16 v[0:3], v[186:189], v[218:221], v[0:3]
	s_setprio 0
	s_barrier
	s_add_i32 s95, 0, 0x18000
	v_add_u32_e32 v144, s95, v169
	s_add_i32 vcc_lo, 0, 0x1c000
	ds_read_b128 v[128:131], v144
	ds_read_b128 v[132:135], v144 offset:1024
	ds_read_b128 v[158:161], v144 offset:2048
	ds_read_b128 v[162:165], v144 offset:3072
	v_add_u32_e32 v144, vcc_lo, v169
	ds_read_b128 v[174:177], v144
	ds_read_b128 v[178:181], v144 offset:1024
	ds_read_b128 v[182:185], v144 offset:2048
	ds_read_b128 v[186:189], v144 offset:3072
	s_add_u32 s90, s90, 0x40000
	s_addc_u32 s91, s91, 0
	s_mov_b32 m0, s61
	v_lshl_add_u64 v[228:229], s[90:91], 0, v[136:137]
	ds_read_b128 v[190:193], v173 offset:32768
	ds_read_b128 v[194:197], v173 offset:33792
	ds_read_b128 v[198:201], v173 offset:34816
	ds_read_b128 v[202:205], v173 offset:35840
	ds_read_b128 v[206:209], v173 offset:36864
	ds_read_b128 v[210:213], v173 offset:37888
	ds_read_b128 v[214:217], v173 offset:38912
	ds_read_b128 v[218:221], v173 offset:39936
	global_load_lds_dwordx4 v[228:229], off
	v_lshl_add_u64 v[228:229], s[90:91], 0, v[140:141]
	s_mov_b32 m0, s62
	s_nop 0
	global_load_lds_dwordx4 v[228:229], off
	s_waitcnt vmcnt(8)
	s_waitcnt lgkmcnt(0)
	s_barrier
	s_setprio 1
	s_waitcnt lgkmcnt(0)
	v_mfma_f32_16x16x32_bf16 v[124:127], v[128:131], v[190:193], v[124:127]
	v_mfma_f32_16x16x32_bf16 v[120:123], v[158:161], v[190:193], v[120:123]
	v_mfma_f32_16x16x32_bf16 v[108:111], v[128:131], v[198:201], v[108:111]
	v_mfma_f32_16x16x32_bf16 v[104:107], v[158:161], v[198:201], v[104:107]
	v_mfma_f32_16x16x32_bf16 v[92:95], v[128:131], v[206:209], v[92:95]
	v_mfma_f32_16x16x32_bf16 v[88:91], v[158:161], v[206:209], v[88:91]
	v_mfma_f32_16x16x32_bf16 v[76:79], v[128:131], v[214:217], v[76:79]
	v_mfma_f32_16x16x32_bf16 v[72:75], v[158:161], v[214:217], v[72:75]
	v_mfma_f32_16x16x32_bf16 v[124:127], v[132:135], v[194:197], v[124:127]
	v_mfma_f32_16x16x32_bf16 v[120:123], v[162:165], v[194:197], v[120:123]
	v_mfma_f32_16x16x32_bf16 v[108:111], v[132:135], v[202:205], v[108:111]
	v_mfma_f32_16x16x32_bf16 v[104:107], v[162:165], v[202:205], v[104:107]
	v_mfma_f32_16x16x32_bf16 v[92:95], v[132:135], v[210:213], v[92:95]
	v_mfma_f32_16x16x32_bf16 v[88:91], v[162:165], v[210:213], v[88:91]
	v_mfma_f32_16x16x32_bf16 v[76:79], v[132:135], v[218:221], v[76:79]
	v_mfma_f32_16x16x32_bf16 v[72:75], v[162:165], v[218:221], v[72:75]
	s_setprio 0
	s_setprio 1
	v_mfma_f32_16x16x32_bf16 v[116:119], v[174:177], v[190:193], v[116:119]
	v_mfma_f32_16x16x32_bf16 v[112:115], v[182:185], v[190:193], v[112:115]
	v_mfma_f32_16x16x32_bf16 v[100:103], v[174:177], v[198:201], v[100:103]
	v_mfma_f32_16x16x32_bf16 v[96:99], v[182:185], v[198:201], v[96:99]
	v_mfma_f32_16x16x32_bf16 v[84:87], v[174:177], v[206:209], v[84:87]
	v_mfma_f32_16x16x32_bf16 v[80:83], v[182:185], v[206:209], v[80:83]
	v_mfma_f32_16x16x32_bf16 v[68:71], v[174:177], v[214:217], v[68:71]
	v_mfma_f32_16x16x32_bf16 v[64:67], v[182:185], v[214:217], v[64:67]
	v_mfma_f32_16x16x32_bf16 v[116:119], v[178:181], v[194:197], v[116:119]
	v_mfma_f32_16x16x32_bf16 v[112:115], v[186:189], v[194:197], v[112:115]
	v_mfma_f32_16x16x32_bf16 v[100:103], v[178:181], v[202:205], v[100:103]
	v_mfma_f32_16x16x32_bf16 v[96:99], v[186:189], v[202:205], v[96:99]
	v_mfma_f32_16x16x32_bf16 v[84:87], v[178:181], v[210:213], v[84:87]
	v_mfma_f32_16x16x32_bf16 v[80:83], v[186:189], v[210:213], v[80:83]
	v_mfma_f32_16x16x32_bf16 v[68:71], v[178:181], v[218:221], v[68:71]
	v_mfma_f32_16x16x32_bf16 v[64:67], v[186:189], v[218:221], v[64:67]
	s_setprio 0
	s_barrier
; #define PG8_STAGE(bufoff, gbase, voff) do { _Pragma("unroll") for (int _i = 0; _i < 2; ++_i) \
;         __builtin_amdgcn_global_load_lds((const unsigned*)((const char*)(gbase) + (voff)[_i]), (PG8_LAS unsigned*)(lds + (bufoff) + ldsw + _i * 8192), 16, 0, 0); } while (0)
; #define PG8_LDA(dst, b, h) do { _Pragma("unroll") for (int m = 0; m < 4; ++m) _Pragma("unroll") for (int k = 0; k < 2; ++k) dst[m][k] = *(const PG8_LAS bf16x8*)(lds + PG8_SA(b, h) + aoff + m * 2048 + k * 1024); } while (0)
; #define PG8_MMA(ai, bj, At, Bt) do { __builtin_amdgcn_s_setprio(1); _Pragma("unroll") for (int m = 0; m < 4; ++m) _Pragma("unroll") for (int n = 0; n < 2; ++n) _Pragma("unroll") for (int k = 0; k < 2; ++k) \
;         acc[ai][bj][m][n] = __builtin_amdgcn_mfma_f32_16x16x32_bf16(Bt[n][k], At[m][k], acc[ai][bj][m][n], 0, 0, 0); __builtin_amdgcn_s_setprio(0); } while (0)
; #define PG8_WAIT_V(n) asm volatile("s_waitcnt vmcnt(" #n ")" ::: "memory")
; #define PG8_WAIT_L(n) asm volatile("s_waitcnt lgkmcnt(" #n ")" ::: "memory")
; #define PG8_BAR __builtin_amdgcn_s_barrier()
; #define PG8_SCHED __builtin_amdgcn_sched_barrier(0)
; template <class Epi, class Sched, bool ALIGN_EPI = false, bool SP2 = false>
; __device__ __forceinline__ void gemm_phase(PG8_LAS unsigned char* lds, const Gemm g, const Sched& S, const Epi& E, int wid_in) {
;     ...
;             PG8_LDA(At, 1, 1); PG8_STAGE(PG8_SB(1, 0), b3, voffB); PG8_STAGE(PG8_SB(1, 1), b3 + hstep, voffB); PG8_STAGE(PG8_SA(1, 0), a3, voffA);
;             PG8_WAIT_V(8); PG8_WAIT_L(0); PG8_BAR; PG8_MMA(1, 0, At, B0); PG8_MMA(1, 1, At, B1); PG8_BAR; PG8_SCHED;
	s_add_i32 s90, s95, s12
	v_lshl_add_u64 v[166:167], v[166:167], 0, s[74:75]
	s_mov_b32 m0, s90
	ds_read_b128 v[190:193], v173 offset:49152
	ds_read_b128 v[194:197], v173 offset:50176
	ds_read_b128 v[198:201], v173 offset:51200
	ds_read_b128 v[202:205], v173 offset:52224
	ds_read_b128 v[206:209], v173 offset:53248
	ds_read_b128 v[210:213], v173 offset:54272
	ds_read_b128 v[214:217], v173 offset:55296
	ds_read_b128 v[218:221], v173 offset:56320
	global_load_lds_dwordx4 v[166:167], off
	s_add_i32 m0, s90, 0x2000
	s_add_u32 s88, s88, 0x40080
	v_lshl_add_u64 v[166:167], v[222:223], 0, s[74:75]
	s_addc_u32 s89, s89, 0
	s_add_i32 s90, vcc_lo, s12
	global_load_lds_dwordx4 v[166:167], off
	v_lshl_add_u64 v[166:167], s[88:89], 0, v[138:139]
	s_mov_b32 m0, s90
	s_nop 0
	global_load_lds_dwordx4 v[166:167], off
	v_lshl_add_u64 v[166:167], s[88:89], 0, v[142:143]
	s_add_i32 m0, s90, 0x2000
	s_nop 0
	global_load_lds_dwordx4 v[166:167], off
	s_waitcnt vmcnt(6)
	s_waitcnt lgkmcnt(0)
	s_barrier
	s_setprio 1
	s_waitcnt lgkmcnt(0)
	v_mfma_f32_16x16x32_bf16 v[60:63], v[128:131], v[190:193], v[60:63]
	v_mfma_f32_16x16x32_bf16 v[56:59], v[158:161], v[190:193], v[56:59]
	v_mfma_f32_16x16x32_bf16 v[44:47], v[128:131], v[198:201], v[44:47]
	v_mfma_f32_16x16x32_bf16 v[40:43], v[158:161], v[198:201], v[40:43]
	v_mfma_f32_16x16x32_bf16 v[28:31], v[128:131], v[206:209], v[28:31]
	v_mfma_f32_16x16x32_bf16 v[24:27], v[158:161], v[206:209], v[24:27]
	v_lshl_add_u64 v[166:167], v[224:225], 0, s[74:75]
	s_mov_b32 m0, s64
	v_mfma_f32_16x16x32_bf16 v[12:15], v[128:131], v[214:217], v[12:15]
	global_load_lds_dwordx4 v[166:167], off
	v_lshl_add_u64 v[166:167], v[226:227], 0, s[74:75]
	s_mov_b32 m0, s65
	v_mfma_f32_16x16x32_bf16 v[8:11], v[158:161], v[214:217], v[8:11]
	global_load_lds_dwordx4 v[166:167], off
	v_mfma_f32_16x16x32_bf16 v[60:63], v[132:135], v[194:197], v[60:63]
	v_mfma_f32_16x16x32_bf16 v[56:59], v[162:165], v[194:197], v[56:59]
	v_mfma_f32_16x16x32_bf16 v[44:47], v[132:135], v[202:205], v[44:47]
	v_mfma_f32_16x16x32_bf16 v[40:43], v[162:165], v[202:205], v[40:43]
	v_mfma_f32_16x16x32_bf16 v[28:31], v[132:135], v[210:213], v[28:31]
	v_mfma_f32_16x16x32_bf16 v[24:27], v[162:165], v[210:213], v[24:27]
	v_mfma_f32_16x16x32_bf16 v[12:15], v[132:135], v[218:221], v[12:15]
	v_mfma_f32_16x16x32_bf16 v[8:11], v[162:165], v[218:221], v[8:11]
	s_setprio 0
	s_setprio 1
	v_mfma_f32_16x16x32_bf16 v[52:55], v[174:177], v[190:193], v[52:55]
	v_mfma_f32_16x16x32_bf16 v[48:51], v[182:185], v[190:193], v[48:51]
	v_mfma_f32_16x16x32_bf16 v[36:39], v[174:177], v[198:201], v[36:39]
	v_mfma_f32_16x16x32_bf16 v[32:35], v[182:185], v[198:201], v[32:35]
	v_mfma_f32_16x16x32_bf16 v[20:23], v[174:177], v[206:209], v[20:23]
	v_mfma_f32_16x16x32_bf16 v[16:19], v[182:185], v[206:209], v[16:19]
	v_mfma_f32_16x16x32_bf16 v[4:7], v[174:177], v[214:217], v[4:7]
	v_mfma_f32_16x16x32_bf16 v[0:3], v[182:185], v[214:217], v[0:3]
	v_mfma_f32_16x16x32_bf16 v[52:55], v[178:181], v[194:197], v[52:55]
	v_mfma_f32_16x16x32_bf16 v[48:51], v[186:189], v[194:197], v[48:51]
	v_mfma_f32_16x16x32_bf16 v[36:39], v[178:181], v[202:205], v[36:39]
	v_mfma_f32_16x16x32_bf16 v[32:35], v[186:189], v[202:205], v[32:35]
	v_mfma_f32_16x16x32_bf16 v[20:23], v[178:181], v[210:213], v[20:23]
	v_mfma_f32_16x16x32_bf16 v[16:19], v[186:189], v[210:213], v[16:19]
	v_mfma_f32_16x16x32_bf16 v[4:7], v[178:181], v[218:221], v[4:7]
	v_mfma_f32_16x16x32_bf16 v[0:3], v[186:189], v[218:221], v[0:3]
	s_setprio 0
	s_barrier
	s_add_i32 s94, s94, 2
	s_add_u32 s68, s68, 0x100
	s_addc_u32 s69, s69, 0
	s_add_u32 s92, s92, 0x100
	s_addc_u32 s93, s93, 0
	s_cmp_gt_u32 s94, 13
	s_cbranch_scc0 .LBB0_227
	s_and_b64 vcc, exec, s[76:77]
	s_cbranch_vccz .LBB0_230
	s_barrier
